# one wave per XCC (workgroups 0-7) starts an L2 write-back midway through the final P7 epilogue, ahead of the end-of-kernel flush
# baseline (speedup 1.0000x reference)
;     __device__ __forceinline__ void operator()(const pg8::f32x4 (&acc)[2][2][4][2], const pg8::Unit& u, int wr, int wc, int fr, int fq) const {
;         const int b = u.pm >> 4;
; #pragma unroll
;         for (int bj = 0; bj < 2; ++bj) { const int c0 = u.pn * 256 + bj * 128 + wc * 32 + 8 * fq; const float* g2p = e.mod + (size_t)b * NMOD + 5 * DM + c0; const f32x4 ga = *(const f32x4*)g2p, gb = *(const f32x4*)(g2p + 4);
; #pragma unroll
;             for (int ai = 0; ai < 2; ++ai)
; #pragma unroll
;                 for (int m = 0; m < 4; ++m) { ACC8(v, ai, bj, m); const size_t off = (size_t)(u.pm * 256 + ai * 128 + wr * 64 + m * 16 + fr) * DM + c0;
;                     f32x4 xa = __builtin_nontemporal_load((const f32x4*)(e.out + off)), xc = __builtin_nontemporal_load((const f32x4*)(e.out + off + 4));
; #pragma unroll
;                     for (int i = 0; i < 4; ++i) { xa[i] += ga[i] * v[i]; xc[i] += gb[i] * v[4 + i]; }
;                     float* dst = e.dump ? e.dump + (off & (size_t)0x7ffff8) : e.out + off;
;                     __builtin_nontemporal_store(xa, (f32x4*)dst); __builtin_nontemporal_store(xc, (f32x4*)(dst + 4)); }
;         }
;     }
.LBB9_856:
	s_ashr_i32 s14, s37, 4
	v_lshl_add_u32 v166, s37, 8, v170
	s_mul_hi_i32 s15, s14, 0x6000
	s_mulk_i32 s14, 0x6000
	v_ashrrev_i32_e32 v167, 31, v166
	s_add_u32 s14, s90, s14
	v_lshlrev_b64 v[152:153], 12, v[166:167]
	v_or_b32_e32 v154, 16, v166
	v_or_b32_e32 v156, 32, v166
	v_or_b32_e32 v158, 48, v166
	v_add_u32_e32 v160, 0x80, v166
	v_add_u32_e32 v162, 0x90, v166
	v_add_u32_e32 v164, 0xa0, v166
	v_add_u32_e32 v166, 0xb0, v166
	v_lshl_or_b32 v168, s38, 8, v172
	s_addc_u32 s15, s91, s15
	v_ashrrev_i32_e32 v155, 31, v154
	v_ashrrev_i32_e32 v157, 31, v156
	v_ashrrev_i32_e32 v159, 31, v158
	v_ashrrev_i32_e32 v161, 31, v160
	v_ashrrev_i32_e32 v163, 31, v162
	v_ashrrev_i32_e32 v165, 31, v164
	v_ashrrev_i32_e32 v167, 31, v166
	s_add_u32 s14, s14, 0x1f45000
	v_ashrrev_i32_e32 v169, 31, v168
	v_lshlrev_b64 v[154:155], 12, v[154:155]
	v_lshlrev_b64 v[156:157], 12, v[156:157]
	v_lshlrev_b64 v[158:159], 12, v[158:159]
	v_lshlrev_b64 v[160:161], 12, v[160:161]
	v_lshlrev_b64 v[162:163], 12, v[162:163]
	v_lshlrev_b64 v[164:165], 12, v[164:165]
	v_lshlrev_b64 v[166:167], 12, v[166:167]
	s_addc_u32 s15, s15, 0
	v_lshlrev_b64 v[232:233], 2, v[168:169]
	v_lshl_add_u64 v[152:153], s[88:89], 0, v[152:153]
	v_lshl_add_u64 v[154:155], s[88:89], 0, v[154:155]
	v_lshl_add_u64 v[156:157], s[88:89], 0, v[156:157]
	v_lshl_add_u64 v[158:159], s[88:89], 0, v[158:159]
	v_lshl_add_u64 v[160:161], s[88:89], 0, v[160:161]
	v_lshl_add_u64 v[162:163], s[88:89], 0, v[162:163]
	v_lshl_add_u64 v[164:165], s[88:89], 0, v[164:165]
	v_lshl_add_u64 v[166:167], s[88:89], 0, v[166:167]
	v_lshl_add_u64 v[132:133], s[14:15], 0, v[232:233]
	v_lshl_add_u64 v[152:153], v[152:153], 0, v[232:233]
	v_lshl_add_u64 v[154:155], v[154:155], 0, v[232:233]
	v_lshl_add_u64 v[156:157], v[156:157], 0, v[232:233]
	v_lshl_add_u64 v[158:159], v[158:159], 0, v[232:233]
	v_lshl_add_u64 v[160:161], v[160:161], 0, v[232:233]
	v_lshl_add_u64 v[162:163], v[162:163], 0, v[232:233]
	v_lshl_add_u64 v[164:165], v[164:165], 0, v[232:233]
	v_lshl_add_u64 v[166:167], v[166:167], 0, v[232:233]
	global_load_dwordx4 v[128:131], v[132:133], off offset:16
	s_nop 0
	global_load_dwordx4 v[132:135], v[132:133], off
	v_or_b32_e32 v248, 0x80, v168
	v_ashrrev_i32_e32 v249, 31, v248
	v_lshl_add_u64 v[248:249], v[248:249], 2, s[14:15]
	global_load_dwordx4 v[240:243], v[248:249], off
	global_load_dwordx4 v[244:247], v[248:249], off offset:16
	global_load_dwordx4 v[176:179], v[152:153], off nt
	global_load_dwordx4 v[180:183], v[152:153], off offset:16 nt
	global_load_dwordx4 v[184:187], v[154:155], off nt
	global_load_dwordx4 v[188:191], v[154:155], off offset:16 nt
	global_load_dwordx4 v[192:195], v[156:157], off nt
	global_load_dwordx4 v[196:199], v[156:157], off offset:16 nt
	global_load_dwordx4 v[200:203], v[158:159], off nt
	global_load_dwordx4 v[204:207], v[158:159], off offset:16 nt
	global_load_dwordx4 v[208:211], v[160:161], off nt
	global_load_dwordx4 v[212:215], v[160:161], off offset:16 nt
	global_load_dwordx4 v[216:219], v[162:163], off nt
	global_load_dwordx4 v[220:223], v[162:163], off offset:16 nt
	global_load_dwordx4 v[224:227], v[164:165], off nt
	global_load_dwordx4 v[228:231], v[164:165], off offset:16 nt
	global_load_dwordx4 v[232:235], v[166:167], off nt
	global_load_dwordx4 v[236:239], v[166:167], off offset:16 nt
	s_and_b64 vcc, exec, s[0:1]
	s_mov_b64 s[0:1], -1
	s_waitcnt vmcnt(8)
	v_pk_fma_f32 v[124:125], v[124:125], v[132:133], v[176:177]
	v_pk_fma_f32 v[126:127], v[126:127], v[134:135], v[178:179]
	v_pk_fma_f32 v[120:121], v[120:121], v[128:129], v[180:181]
	v_pk_fma_f32 v[122:123], v[122:123], v[130:131], v[182:183]
	v_pk_fma_f32 v[116:117], v[116:117], v[132:133], v[184:185]
	v_pk_fma_f32 v[118:119], v[118:119], v[134:135], v[186:187]
	v_pk_fma_f32 v[112:113], v[112:113], v[128:129], v[188:189]
	v_pk_fma_f32 v[114:115], v[114:115], v[130:131], v[190:191]
	v_pk_fma_f32 v[108:109], v[108:109], v[132:133], v[192:193]
	v_pk_fma_f32 v[110:111], v[110:111], v[134:135], v[194:195]
	v_pk_fma_f32 v[104:105], v[104:105], v[128:129], v[196:197]
	v_pk_fma_f32 v[106:107], v[106:107], v[130:131], v[198:199]
	v_pk_fma_f32 v[100:101], v[100:101], v[132:133], v[200:201]
	v_pk_fma_f32 v[102:103], v[102:103], v[134:135], v[202:203]
	v_pk_fma_f32 v[96:97], v[96:97], v[128:129], v[204:205]
	v_pk_fma_f32 v[98:99], v[98:99], v[130:131], v[206:207]
	global_load_dwordx4 v[176:179], v[152:153], off offset:512 nt
	global_load_dwordx4 v[180:183], v[152:153], off offset:528 nt
	global_load_dwordx4 v[184:187], v[154:155], off offset:512 nt
	global_load_dwordx4 v[188:191], v[154:155], off offset:528 nt
	global_load_dwordx4 v[192:195], v[156:157], off offset:512 nt
	global_load_dwordx4 v[196:199], v[156:157], off offset:528 nt
	global_load_dwordx4 v[200:203], v[158:159], off offset:512 nt
	global_load_dwordx4 v[204:207], v[158:159], off offset:528 nt
	global_store_dwordx4 v[152:153], v[124:127], off
	global_store_dwordx4 v[152:153], v[120:123], off offset:16
	global_store_dwordx4 v[154:155], v[116:119], off
	global_store_dwordx4 v[154:155], v[112:115], off offset:16
	global_store_dwordx4 v[156:157], v[108:111], off
	global_store_dwordx4 v[156:157], v[104:107], off offset:16
	global_store_dwordx4 v[158:159], v[100:103], off
	global_store_dwordx4 v[158:159], v[96:99], off offset:16
	s_waitcnt vmcnt(16)
;     __device__ __forceinline__ void operator()(const pg8::f32x4 (&acc)[2][2][4][2], const pg8::Unit& u, int wr, int wc, int fr, int fq) const {
;         const int b = u.pm >> 4;
; #pragma unroll
;         for (int bj = 0; bj < 2; ++bj) { const int c0 = u.pn * 256 + bj * 128 + wc * 32 + 8 * fq; const float* g2p = e.mod + (size_t)b * NMOD + 5 * DM + c0; const f32x4 ga = *(const f32x4*)g2p, gb = *(const f32x4*)(g2p + 4);
; #pragma unroll
;             for (int ai = 0; ai < 2; ++ai)
; #pragma unroll
;                 for (int m = 0; m < 4; ++m) { ACC8(v, ai, bj, m); const size_t off = (size_t)(u.pm * 256 + ai * 128 + wr * 64 + m * 16 + fr) * DM + c0;
;                     f32x4 xa = __builtin_nontemporal_load((const f32x4*)(e.out + off)), xc = __builtin_nontemporal_load((const f32x4*)(e.out + off + 4));
; #pragma unroll
;                     for (int i = 0; i < 4; ++i) { xa[i] += ga[i] * v[i]; xc[i] += gb[i] * v[4 + i]; }
;                     float* dst = e.dump ? e.dump + (off & (size_t)0x7ffff8) : e.out + off;
;                     __builtin_nontemporal_store(xa, (f32x4*)dst); __builtin_nontemporal_store(xc, (f32x4*)(dst + 4)); }
;         }
;     }
	v_pk_fma_f32 v[92:93], v[92:93], v[132:133], v[208:209]
	v_pk_fma_f32 v[94:95], v[94:95], v[134:135], v[210:211]
	v_pk_fma_f32 v[88:89], v[88:89], v[128:129], v[212:213]
	v_pk_fma_f32 v[90:91], v[90:91], v[130:131], v[214:215]
	v_pk_fma_f32 v[84:85], v[84:85], v[132:133], v[216:217]
	v_pk_fma_f32 v[86:87], v[86:87], v[134:135], v[218:219]
	v_pk_fma_f32 v[80:81], v[80:81], v[128:129], v[220:221]
	v_pk_fma_f32 v[82:83], v[82:83], v[130:131], v[222:223]
	v_pk_fma_f32 v[76:77], v[76:77], v[132:133], v[224:225]
	v_pk_fma_f32 v[78:79], v[78:79], v[134:135], v[226:227]
	v_pk_fma_f32 v[72:73], v[72:73], v[128:129], v[228:229]
	v_pk_fma_f32 v[74:75], v[74:75], v[130:131], v[230:231]
	v_pk_fma_f32 v[68:69], v[68:69], v[132:133], v[232:233]
	v_pk_fma_f32 v[70:71], v[70:71], v[134:135], v[234:235]
	v_pk_fma_f32 v[64:65], v[64:65], v[128:129], v[236:237]
	v_pk_fma_f32 v[66:67], v[66:67], v[130:131], v[238:239]
	global_load_dwordx4 v[208:211], v[160:161], off offset:512 nt
	global_load_dwordx4 v[212:215], v[160:161], off offset:528 nt
	global_load_dwordx4 v[216:219], v[162:163], off offset:512 nt
	global_load_dwordx4 v[220:223], v[162:163], off offset:528 nt
	global_load_dwordx4 v[224:227], v[164:165], off offset:512 nt
	global_load_dwordx4 v[228:231], v[164:165], off offset:528 nt
	global_load_dwordx4 v[232:235], v[166:167], off offset:512 nt
	global_load_dwordx4 v[236:239], v[166:167], off offset:528 nt
	global_store_dwordx4 v[160:161], v[92:95], off
	global_store_dwordx4 v[160:161], v[88:91], off offset:16
	global_store_dwordx4 v[162:163], v[84:87], off
	global_store_dwordx4 v[162:163], v[80:83], off offset:16
	global_store_dwordx4 v[164:165], v[76:79], off
	global_store_dwordx4 v[164:165], v[72:75], off offset:16
	global_store_dwordx4 v[166:167], v[68:71], off
	global_store_dwordx4 v[166:167], v[64:67], off offset:16
	s_cmp_lt_u32 s97, 8
	s_cbranch_scc0 .Lp7wb_skip
	s_cmp_lg_u64 s[80:81], 0
	s_cbranch_scc0 .Lp7wb_skip
	buffer_wbl2 sc1
.Lp7wb_skip:
	s_waitcnt vmcnt(24)
	v_pk_fma_f32 v[60:61], v[60:61], v[240:241], v[176:177]
	v_pk_fma_f32 v[62:63], v[62:63], v[242:243], v[178:179]
	v_pk_fma_f32 v[56:57], v[56:57], v[244:245], v[180:181]
	v_pk_fma_f32 v[58:59], v[58:59], v[246:247], v[182:183]
	v_pk_fma_f32 v[52:53], v[52:53], v[240:241], v[184:185]
	v_pk_fma_f32 v[54:55], v[54:55], v[242:243], v[186:187]
	v_pk_fma_f32 v[48:49], v[48:49], v[244:245], v[188:189]
	v_pk_fma_f32 v[50:51], v[50:51], v[246:247], v[190:191]
	v_pk_fma_f32 v[44:45], v[44:45], v[240:241], v[192:193]
	v_pk_fma_f32 v[46:47], v[46:47], v[242:243], v[194:195]
	v_pk_fma_f32 v[40:41], v[40:41], v[244:245], v[196:197]
	v_pk_fma_f32 v[42:43], v[42:43], v[246:247], v[198:199]
	v_pk_fma_f32 v[36:37], v[36:37], v[240:241], v[200:201]
	v_pk_fma_f32 v[38:39], v[38:39], v[242:243], v[202:203]
	v_pk_fma_f32 v[32:33], v[32:33], v[244:245], v[204:205]
	v_pk_fma_f32 v[34:35], v[34:35], v[246:247], v[206:207]
	global_store_dwordx4 v[152:153], v[60:63], off offset:512
	global_store_dwordx4 v[152:153], v[56:59], off offset:528
	global_store_dwordx4 v[154:155], v[52:55], off offset:512
	global_store_dwordx4 v[154:155], v[48:51], off offset:528
	global_store_dwordx4 v[156:157], v[44:47], off offset:512
	global_store_dwordx4 v[156:157], v[40:43], off offset:528
	global_store_dwordx4 v[158:159], v[36:39], off offset:512
	global_store_dwordx4 v[158:159], v[32:35], off offset:528
	s_waitcnt vmcnt(16)
	v_pk_fma_f32 v[28:29], v[28:29], v[240:241], v[208:209]
	v_pk_fma_f32 v[30:31], v[30:31], v[242:243], v[210:211]
	v_pk_fma_f32 v[24:25], v[24:25], v[244:245], v[212:213]
	v_pk_fma_f32 v[26:27], v[26:27], v[246:247], v[214:215]
	v_pk_fma_f32 v[20:21], v[20:21], v[240:241], v[216:217]
	v_pk_fma_f32 v[22:23], v[22:23], v[242:243], v[218:219]
	v_pk_fma_f32 v[16:17], v[16:17], v[244:245], v[220:221]
	v_pk_fma_f32 v[18:19], v[18:19], v[246:247], v[222:223]
	v_pk_fma_f32 v[12:13], v[12:13], v[240:241], v[224:225]
	v_pk_fma_f32 v[14:15], v[14:15], v[242:243], v[226:227]
	v_pk_fma_f32 v[8:9], v[8:9], v[244:245], v[228:229]
	v_pk_fma_f32 v[10:11], v[10:11], v[246:247], v[230:231]
	v_pk_fma_f32 v[4:5], v[4:5], v[240:241], v[232:233]
	v_pk_fma_f32 v[6:7], v[6:7], v[242:243], v[234:235]
	v_pk_fma_f32 v[0:1], v[0:1], v[244:245], v[236:237]
	v_pk_fma_f32 v[2:3], v[2:3], v[246:247], v[238:239]
	global_store_dwordx4 v[160:161], v[28:31], off offset:512
	global_store_dwordx4 v[160:161], v[24:27], off offset:528
	global_store_dwordx4 v[162:163], v[20:23], off offset:512
	global_store_dwordx4 v[162:163], v[16:19], off offset:528
	global_store_dwordx4 v[164:165], v[12:15], off offset:512
	global_store_dwordx4 v[164:165], v[8:11], off offset:528
	global_store_dwordx4 v[166:167], v[4:7], off offset:512
	global_store_dwordx4 v[166:167], v[0:3], off offset:528
	s_cbranch_vccnz .LBB9_841
	s_andn2_b64 vcc, exec, s[6:7]
	s_cbranch_vccnz .LBB9_840
	s_barrier
	s_branch .LBB9_840
